# WG stagger config G: groups chosen by blockIdx bits 0,1 (whole XCDs shifted against each other) instead of bits 3,4
# baseline (speedup 1.0000x reference)
;   DI bf16_t* wt_in0() const { return (bf16_t*)(ws + OFF_WT_IN0); }
;   DI bf16_t* h() const { return (bf16_t*)(ws + OFF_H); }
; DI void phase_gemm_in0(const Params& p, char* smem) {
;   u32x4 ra[4], rb[4]; bool pre = false;
;   for (int t = blockIdx.x; t < 64 * 16; t += gridDim.x) {
;     const int mt = t & 63, nt = t >> 6, tn = t + gridDim.x;
;     const bool has_next = tn < 64 * 16;
;     const GTile tl{p.h(), D, p.wt_in0(), D, D, mt * 256, nt * 256}, nx{p.h(), D, p.wt_in0(), D, D, (tn & 63) * 256, (tn >> 6) * 256};
.Lgs_185:
	s_or_b64 exec, exec, s[0:1]
	s_bitcmp1_b32 s84, 0
	s_cbranch_scc0 .Lstag_1_0
	s_sleep 64
.Lstag_1_0:
	s_bitcmp1_b32 s84, 1
	s_cbranch_scc0 .Lstag_1_1
	s_sleep 127

;   DI bf16_t* h() const { return (bf16_t*)(ws + OFF_H); }
; DI void phase_gemm_out(const Params& p, char* smem, const bf16_t* Wt, const float* R, float* O) {
;   u32x4 ra[4], rb[4]; bool pre = false;
;   for (int t = blockIdx.x; t < 64 * 8; t += gridDim.x) {
;     const int mt = t & 63, nt = t >> 6, tn = t + gridDim.x;
;     const bool has_next = tn < 64 * 8;
;     const GTile tl{p.h(), D, Wt, D, D, mt * 256, nt * 256}, nx{p.h(), D, Wt, D, D, (tn & 63) * 256, (tn >> 6) * 256};
;     WAVE_GEOM;
.LBB0_742:
	s_or_b64 exec, exec, s[0:1]
	s_bitcmp1_b32 s84, 0
	s_cbranch_scc0 .Lstag_6_0
	s_sleep 127
.Lstag_6_0:
	s_bitcmp1_b32 s84, 1
	s_cbranch_scc0 .Lstag_6_1
	s_sleep 127
	s_sleep 127
